# GEMM1 K loop: third staging register set, global loads run three K tiles ahead (was two)
# baseline (speedup 1.0000x reference)
.LBB0_208:
	s_lshl_b32 s4, s8, 8
	s_ashr_i32 s5, s4, 31
	v_mov_b32_e32 v58, v212
	s_lshl_b64 s[10:11], s[4:5], 11
	s_add_u32 s10, s45, s10
	v_ashrrev_i32_e32 v30, 3, v58
	v_ashrrev_i32_e32 v31, 31, v30
	s_addc_u32 s11, s46, s11
	v_lshlrev_b64 v[2:3], 11, v[30:31]
	v_lshlrev_b32_e32 v6, 4, v58
	v_lshl_add_u64 v[4:5], s[10:11], 0, v[2:3]
	v_and_b32_e32 v98, 0x70, v6
	v_lshl_add_u64 v[102:103], v[4:5], 0, v[98:99]
	s_mul_i32 s6, s9, 0xc0
	v_add_co_u32_e32 v106, vcc, s54, v102
	s_ashr_i32 s7, s6, 31
	s_nop 0
	v_addc_co_u32_e32 v107, vcc, 0, v103, vcc
	s_lshl_b64 s[12:13], s[6:7], 11
	v_add_co_u32_e32 v108, vcc, s55, v102
	s_add_u32 s12, s47, s12
	s_nop 0
	v_addc_co_u32_e32 v109, vcc, 0, v103, vcc
	s_mov_b32 s3, 0x60000
	s_addc_u32 s13, s48, s13
	v_add_co_u32_e32 v110, vcc, s3, v102
	v_lshl_add_u64 v[2:3], s[12:13], 0, v[2:3]
	s_nop 0
	v_addc_co_u32_e32 v111, vcc, 0, v103, vcc
	v_lshl_add_u64 v[104:105], v[2:3], 0, v[98:99]
	global_load_dwordx4 v[2:5], v[102:103], off
	global_load_dwordx4 v[6:9], v[106:107], off
	global_load_dwordx4 v[10:13], v[108:109], off
	global_load_dwordx4 v[14:17], v[110:111], off
	global_load_dwordx4 v[18:21], v[104:105], off
	v_add_co_u32_e32 v112, vcc, s54, v104
	v_mad_u64_u32 v[114:115], s[10:11], v30, s50, v[98:99]
	s_nop 0
	v_addc_co_u32_e32 v113, vcc, 0, v105, vcc
	v_add_co_u32_e32 v116, vcc, s55, v104
	global_load_dwordx4 v[22:25], v[112:113], off
	s_nop 0
	v_addc_co_u32_e32 v117, vcc, 0, v105, vcc
	global_load_dwordx4 v[26:29], v[116:117], off
	global_load_dwordx4 v[30:33], v[102:103], off offset:128
	global_load_dwordx4 v[34:37], v[106:107], off offset:128
	global_load_dwordx4 v[38:41], v[108:109], off offset:128
	global_load_dwordx4 v[42:45], v[110:111], off offset:128
	global_load_dwordx4 v[46:49], v[104:105], off offset:128
	global_load_dwordx4 v[50:53], v[112:113], off offset:128
	global_load_dwordx4 v[54:57], v[116:117], off offset:128
	global_load_dwordx4 v[120:123], v[106:107], off offset:256
	global_load_dwordx4 v[136:139], v[108:109], off offset:256
	global_load_dwordx4 v[140:143], v[102:103], off offset:256
	global_load_dwordx4 v[144:147], v[104:105], off offset:256
	global_load_dwordx4 v[148:151], v[110:111], off offset:256
	global_load_dwordx4 v[152:155], v[112:113], off offset:256
	global_load_dwordx4 v[156:159], v[116:117], off offset:256
	s_mov_b32 s3, 0xfffffc0
	v_add_u32_e32 v119, 0x12000, v114
	s_waitcnt vmcnt(20)
	ds_write_b128 v114, v[2:5]
	s_waitcnt vmcnt(19)
	ds_write_b128 v114, v[6:9] offset:9216
	s_waitcnt vmcnt(18)
	ds_write_b128 v114, v[10:13] offset:18432
	s_waitcnt vmcnt(17)
	ds_write_b128 v114, v[14:17] offset:27648
	s_waitcnt vmcnt(16)
	ds_write_b128 v114, v[18:21] offset:36864
	s_waitcnt vmcnt(15)
	ds_write_b128 v114, v[22:25] offset:46080
	s_waitcnt vmcnt(14)
	ds_write_b128 v114, v[26:29] offset:55296
	s_waitcnt lgkmcnt(0)
	s_barrier
	global_load_dwordx4 v[162:165], v[106:107], off offset:384
	global_load_dwordx4 v[166:169], v[108:109], off offset:384
	global_load_dwordx4 v[170:173], v[102:103], off offset:384
	global_load_dwordx4 v[174:177], v[104:105], off offset:384
	global_load_dwordx4 v[178:181], v[110:111], off offset:384
	global_load_dwordx4 v[182:185], v[112:113], off offset:384
	global_load_dwordx4 v[186:189], v[116:117], off offset:384
	v_and_b32_e32 v3, 31, v58
	v_lshrrev_b32_e32 v2, 1, v58
	v_and_or_b32 v4, v2, s3, v3
	v_bfe_i32 v5, v58, 6, 1
	s_movk_i32 s3, 0x60
	v_and_b32_e32 v2, 16, v2
	v_and_or_b32 v3, v5, s3, v3
	v_mad_u32_u24 v115, v3, s50, v2
	v_add_u32_e32 v98, 0x12000, v115
	s_waitcnt vmcnt(20)
	ds_write_b128 v119, v[30:33]
	s_waitcnt vmcnt(19)
	ds_write_b128 v119, v[34:37] offset:9216
	s_waitcnt vmcnt(18)
	ds_write_b128 v119, v[38:41] offset:18432
	s_waitcnt vmcnt(17)
	ds_write_b128 v119, v[42:45] offset:27648
	s_waitcnt vmcnt(16)
	ds_write_b128 v119, v[46:49] offset:36864
	s_waitcnt vmcnt(15)
	ds_write_b128 v119, v[50:53] offset:46080
	s_waitcnt vmcnt(14)
	ds_write_b128 v119, v[54:57] offset:55296
	v_mad_u64_u32 v[100:101], s[10:11], v4, s50, v[2:3]
	ds_read_b128 v[18:21], v115 offset:36864
	ds_read_b128 v[214:217], v115 offset:36896
	ds_read_b128 v[22:25], v115 offset:41472
	ds_read_b128 v[218:221], v115 offset:41504
	ds_read_b128 v[26:29], v115 offset:46080
	ds_read_b128 v[222:225], v115 offset:46112
	ds_read_b128 v[2:5], v100
	ds_read_b128 v[226:229], v100 offset:32
	ds_read_b128 v[30:33], v100 offset:4608
	ds_read_b128 v[230:233], v100 offset:4640
	s_setprio 1
	s_waitcnt lgkmcnt(3)
	v_mfma_f32_32x32x16_bf16 v[82:97], v[2:5], v[18:21], 0
	v_mfma_f32_32x32x16_bf16 v[50:65], v[2:5], v[22:25], 0
	v_mfma_f32_32x32x16_bf16 v[2:17], v[2:5], v[26:29], 0
	s_waitcnt lgkmcnt(1)
	v_mfma_f32_32x32x16_bf16 v[66:81], v[30:33], v[18:21], 0
	v_mfma_f32_32x32x16_bf16 v[34:49], v[30:33], v[22:25], 0
	v_mfma_f32_32x32x16_bf16 v[18:33], v[30:33], v[26:29], 0
	s_setprio 0
	ds_read_b128 v[234:237], v115 offset:36928
	ds_read_b128 v[238:241], v115 offset:41536
	ds_read_b128 v[190:193], v115 offset:46144
	ds_read_b128 v[194:197], v100 offset:64
	ds_read_b128 v[198:201], v100 offset:4672
	s_setprio 1
	v_mfma_f32_32x32x16_bf16 v[82:97], v[226:229], v[214:217], v[82:97]
	v_mfma_f32_32x32x16_bf16 v[50:65], v[226:229], v[218:221], v[50:65]
	v_mfma_f32_32x32x16_bf16 v[2:17], v[226:229], v[222:225], v[2:17]
	s_waitcnt lgkmcnt(5)
	v_mfma_f32_32x32x16_bf16 v[66:81], v[230:233], v[214:217], v[66:81]
	v_mfma_f32_32x32x16_bf16 v[34:49], v[230:233], v[218:221], v[34:49]
	v_mfma_f32_32x32x16_bf16 v[18:33], v[230:233], v[222:225], v[18:33]
	s_setprio 0
	ds_read_b128 v[214:217], v115 offset:36960
	ds_read_b128 v[218:221], v115 offset:41568
	ds_read_b128 v[222:225], v115 offset:46176
	ds_read_b128 v[226:229], v100 offset:96
	ds_read_b128 v[230:233], v100 offset:4704
	s_setprio 1
	s_waitcnt lgkmcnt(6)
	v_mfma_f32_32x32x16_bf16 v[82:97], v[194:197], v[234:237], v[82:97]
	v_mfma_f32_32x32x16_bf16 v[50:65], v[194:197], v[238:241], v[50:65]
	v_mfma_f32_32x32x16_bf16 v[2:17], v[194:197], v[190:193], v[2:17]
	s_waitcnt lgkmcnt(5)
	v_mfma_f32_32x32x16_bf16 v[66:81], v[198:201], v[234:237], v[66:81]
	v_mfma_f32_32x32x16_bf16 v[34:49], v[198:201], v[238:241], v[34:49]
	v_mfma_f32_32x32x16_bf16 v[18:33], v[198:201], v[190:193], v[18:33]
	s_setprio 0
	s_setprio 1
	s_waitcnt lgkmcnt(1)
	v_mfma_f32_32x32x16_bf16 v[82:97], v[226:229], v[214:217], v[82:97]
	v_mfma_f32_32x32x16_bf16 v[50:65], v[226:229], v[218:221], v[50:65]
	v_mfma_f32_32x32x16_bf16 v[2:17], v[226:229], v[222:225], v[2:17]
	s_waitcnt lgkmcnt(0)
	v_mfma_f32_32x32x16_bf16 v[66:81], v[230:233], v[214:217], v[66:81]
	v_mfma_f32_32x32x16_bf16 v[34:49], v[230:233], v[218:221], v[34:49]
	v_mfma_f32_32x32x16_bf16 v[18:33], v[230:233], v[222:225], v[18:33]
	s_setprio 0
	s_barrier
	global_load_dwordx4 v[214:217], v[106:107], off offset:512
	global_load_dwordx4 v[218:221], v[108:109], off offset:512
	global_load_dwordx4 v[222:225], v[102:103], off offset:512
	global_load_dwordx4 v[226:229], v[104:105], off offset:512
	global_load_dwordx4 v[230:233], v[110:111], off offset:512
	global_load_dwordx4 v[234:237], v[112:113], off offset:512
	global_load_dwordx4 v[238:241], v[116:117], off offset:512
	s_waitcnt vmcnt(18)
	ds_write_b128 v114, v[140:143]
	ds_write_b128 v114, v[120:123] offset:9216
	ds_write_b128 v114, v[136:139] offset:18432
	s_waitcnt vmcnt(16)
	ds_write_b128 v114, v[148:151] offset:27648
	ds_write_b128 v114, v[144:147] offset:36864
	s_waitcnt vmcnt(15)
	ds_write_b128 v114, v[152:155] offset:46080
	s_waitcnt vmcnt(14)
	ds_write_b128 v114, v[156:159] offset:55296
	v_add_u32_e32 v101, 0x12000, v100
	ds_read_b128 v[120:123], v98 offset:36864
	ds_read_b128 v[136:139], v98 offset:36896
	ds_read_b128 v[140:143], v98 offset:41472
	ds_read_b128 v[144:147], v98 offset:41504
	ds_read_b128 v[148:151], v98 offset:46080
	ds_read_b128 v[152:155], v98 offset:46112
	ds_read_b128 v[156:159], v101
	ds_read_b128 v[190:193], v101 offset:32
	ds_read_b128 v[194:197], v101 offset:4608
	ds_read_b128 v[198:201], v101 offset:4640
	s_setprio 1
	s_waitcnt lgkmcnt(3)
	v_mfma_f32_32x32x16_bf16 v[82:97], v[156:159], v[120:123], v[82:97]
	v_mfma_f32_32x32x16_bf16 v[50:65], v[156:159], v[140:143], v[50:65]
	v_mfma_f32_32x32x16_bf16 v[2:17], v[156:159], v[148:151], v[2:17]
	s_waitcnt lgkmcnt(1)
	v_mfma_f32_32x32x16_bf16 v[66:81], v[194:197], v[120:123], v[66:81]
	v_mfma_f32_32x32x16_bf16 v[34:49], v[194:197], v[140:143], v[34:49]
	v_mfma_f32_32x32x16_bf16 v[18:33], v[194:197], v[148:151], v[18:33]
	s_setprio 0
	ds_read_b128 v[120:123], v98 offset:36928
	ds_read_b128 v[140:143], v98 offset:41536
	ds_read_b128 v[148:151], v98 offset:46144
	ds_read_b128 v[156:159], v101 offset:64
	ds_read_b128 v[194:197], v101 offset:4672
	s_setprio 1
	v_mfma_f32_32x32x16_bf16 v[82:97], v[190:193], v[136:139], v[82:97]
	v_mfma_f32_32x32x16_bf16 v[50:65], v[190:193], v[144:147], v[50:65]
	v_mfma_f32_32x32x16_bf16 v[2:17], v[190:193], v[152:155], v[2:17]
	s_waitcnt lgkmcnt(5)
	v_mfma_f32_32x32x16_bf16 v[66:81], v[198:201], v[136:139], v[66:81]
	v_mfma_f32_32x32x16_bf16 v[34:49], v[198:201], v[144:147], v[34:49]
	v_mfma_f32_32x32x16_bf16 v[18:33], v[198:201], v[152:155], v[18:33]
	s_setprio 0
	ds_read_b128 v[136:139], v98 offset:36960
	ds_read_b128 v[144:147], v98 offset:41568
	ds_read_b128 v[152:155], v98 offset:46176
	ds_read_b128 v[190:193], v101 offset:96
	ds_read_b128 v[198:201], v101 offset:4704
	s_setprio 1
	s_waitcnt lgkmcnt(6)
	v_mfma_f32_32x32x16_bf16 v[82:97], v[156:159], v[120:123], v[82:97]
	v_mfma_f32_32x32x16_bf16 v[50:65], v[156:159], v[140:143], v[50:65]
	v_mfma_f32_32x32x16_bf16 v[2:17], v[156:159], v[148:151], v[2:17]
	s_waitcnt lgkmcnt(5)
	v_mfma_f32_32x32x16_bf16 v[66:81], v[194:197], v[120:123], v[66:81]
	v_mfma_f32_32x32x16_bf16 v[34:49], v[194:197], v[140:143], v[34:49]
	v_mfma_f32_32x32x16_bf16 v[18:33], v[194:197], v[148:151], v[18:33]
	s_setprio 0
	s_setprio 1
	s_waitcnt lgkmcnt(1)
	v_mfma_f32_32x32x16_bf16 v[82:97], v[190:193], v[136:139], v[82:97]
	v_mfma_f32_32x32x16_bf16 v[50:65], v[190:193], v[144:147], v[50:65]
	v_mfma_f32_32x32x16_bf16 v[2:17], v[190:193], v[152:155], v[2:17]
	s_waitcnt lgkmcnt(0)
	v_mfma_f32_32x32x16_bf16 v[66:81], v[198:201], v[136:139], v[66:81]
	v_mfma_f32_32x32x16_bf16 v[34:49], v[198:201], v[144:147], v[34:49]
	v_mfma_f32_32x32x16_bf16 v[18:33], v[198:201], v[152:155], v[18:33]
	s_setprio 0
	s_barrier
	global_load_dwordx4 v[120:123], v[106:107], off offset:640
	global_load_dwordx4 v[136:139], v[108:109], off offset:640
	global_load_dwordx4 v[140:143], v[102:103], off offset:640
	global_load_dwordx4 v[144:147], v[104:105], off offset:640
	global_load_dwordx4 v[148:151], v[110:111], off offset:640
	global_load_dwordx4 v[152:155], v[112:113], off offset:640
	global_load_dwordx4 v[156:159], v[116:117], off offset:640
	s_waitcnt vmcnt(18)
	ds_write_b128 v119, v[170:173]
	ds_write_b128 v119, v[162:165] offset:9216
	ds_write_b128 v119, v[166:169] offset:18432
	s_waitcnt vmcnt(16)
	ds_write_b128 v119, v[178:181] offset:27648
	ds_write_b128 v119, v[174:177] offset:36864
	s_waitcnt vmcnt(15)
	ds_write_b128 v119, v[182:185] offset:46080
	s_waitcnt vmcnt(14)
	ds_write_b128 v119, v[186:189] offset:55296
	ds_read_b128 v[162:165], v115 offset:36864
	ds_read_b128 v[166:169], v115 offset:36896
	ds_read_b128 v[170:173], v115 offset:41472
	ds_read_b128 v[174:177], v115 offset:41504
	ds_read_b128 v[178:181], v115 offset:46080
	ds_read_b128 v[182:185], v115 offset:46112
	ds_read_b128 v[186:189], v100
	ds_read_b128 v[190:193], v100 offset:32
	ds_read_b128 v[194:197], v100 offset:4608
	ds_read_b128 v[198:201], v100 offset:4640
	s_setprio 1
	s_waitcnt lgkmcnt(3)
	v_mfma_f32_32x32x16_bf16 v[82:97], v[186:189], v[162:165], v[82:97]
	v_mfma_f32_32x32x16_bf16 v[50:65], v[186:189], v[170:173], v[50:65]
	v_mfma_f32_32x32x16_bf16 v[2:17], v[186:189], v[178:181], v[2:17]
	s_waitcnt lgkmcnt(1)
	v_mfma_f32_32x32x16_bf16 v[66:81], v[194:197], v[162:165], v[66:81]
	v_mfma_f32_32x32x16_bf16 v[34:49], v[194:197], v[170:173], v[34:49]
	v_mfma_f32_32x32x16_bf16 v[18:33], v[194:197], v[178:181], v[18:33]
	s_setprio 0
	ds_read_b128 v[162:165], v115 offset:36928
	ds_read_b128 v[170:173], v115 offset:41536
	ds_read_b128 v[178:181], v115 offset:46144
	ds_read_b128 v[186:189], v100 offset:64
	ds_read_b128 v[194:197], v100 offset:4672
	s_setprio 1
	v_mfma_f32_32x32x16_bf16 v[82:97], v[190:193], v[166:169], v[82:97]
	v_mfma_f32_32x32x16_bf16 v[50:65], v[190:193], v[174:177], v[50:65]
	v_mfma_f32_32x32x16_bf16 v[2:17], v[190:193], v[182:185], v[2:17]
	s_waitcnt lgkmcnt(5)
	v_mfma_f32_32x32x16_bf16 v[66:81], v[198:201], v[166:169], v[66:81]
	v_mfma_f32_32x32x16_bf16 v[34:49], v[198:201], v[174:177], v[34:49]
	v_mfma_f32_32x32x16_bf16 v[18:33], v[198:201], v[182:185], v[18:33]
	s_setprio 0
	ds_read_b128 v[166:169], v115 offset:36960
	ds_read_b128 v[174:177], v115 offset:41568
	ds_read_b128 v[182:185], v115 offset:46176
	ds_read_b128 v[190:193], v100 offset:96
	ds_read_b128 v[198:201], v100 offset:4704
	s_setprio 1
	s_waitcnt lgkmcnt(6)
	v_mfma_f32_32x32x16_bf16 v[82:97], v[186:189], v[162:165], v[82:97]
	v_mfma_f32_32x32x16_bf16 v[50:65], v[186:189], v[170:173], v[50:65]
	v_mfma_f32_32x32x16_bf16 v[2:17], v[186:189], v[178:181], v[2:17]
	s_waitcnt lgkmcnt(5)
	v_mfma_f32_32x32x16_bf16 v[66:81], v[194:197], v[162:165], v[66:81]
	v_mfma_f32_32x32x16_bf16 v[34:49], v[194:197], v[170:173], v[34:49]
	v_mfma_f32_32x32x16_bf16 v[18:33], v[194:197], v[178:181], v[18:33]
	s_setprio 0
	s_setprio 1
	s_waitcnt lgkmcnt(1)
	v_mfma_f32_32x32x16_bf16 v[82:97], v[190:193], v[166:169], v[82:97]
	v_mfma_f32_32x32x16_bf16 v[50:65], v[190:193], v[174:177], v[50:65]
	v_mfma_f32_32x32x16_bf16 v[2:17], v[190:193], v[182:185], v[2:17]
	s_waitcnt lgkmcnt(0)
	v_mfma_f32_32x32x16_bf16 v[66:81], v[198:201], v[166:169], v[66:81]
	v_mfma_f32_32x32x16_bf16 v[34:49], v[198:201], v[174:177], v[34:49]
	v_mfma_f32_32x32x16_bf16 v[18:33], v[198:201], v[182:185], v[18:33]
	s_setprio 0
	s_barrier
	global_load_dwordx4 v[162:165], v[106:107], off offset:768
	global_load_dwordx4 v[166:169], v[108:109], off offset:768
	global_load_dwordx4 v[170:173], v[102:103], off offset:768
	global_load_dwordx4 v[174:177], v[104:105], off offset:768
	global_load_dwordx4 v[178:181], v[110:111], off offset:768
	global_load_dwordx4 v[182:185], v[112:113], off offset:768
	global_load_dwordx4 v[186:189], v[116:117], off offset:768
	s_waitcnt vmcnt(18)
	ds_write_b128 v114, v[222:225]
	ds_write_b128 v114, v[214:217] offset:9216
	ds_write_b128 v114, v[218:221] offset:18432
	s_waitcnt vmcnt(16)
	ds_write_b128 v114, v[230:233] offset:27648
	ds_write_b128 v114, v[226:229] offset:36864
	s_waitcnt vmcnt(15)
	ds_write_b128 v114, v[234:237] offset:46080
	s_waitcnt vmcnt(14)
	ds_write_b128 v114, v[238:241] offset:55296
	ds_read_b128 v[214:217], v98 offset:36864
	ds_read_b128 v[218:221], v98 offset:36896
	ds_read_b128 v[222:225], v98 offset:41472
	ds_read_b128 v[226:229], v98 offset:41504
	ds_read_b128 v[230:233], v98 offset:46080
	ds_read_b128 v[234:237], v98 offset:46112
	ds_read_b128 v[238:241], v101
	ds_read_b128 v[190:193], v101 offset:32
	ds_read_b128 v[194:197], v101 offset:4608
	ds_read_b128 v[198:201], v101 offset:4640
	s_setprio 1
	s_waitcnt lgkmcnt(3)
	v_mfma_f32_32x32x16_bf16 v[82:97], v[238:241], v[214:217], v[82:97]
	v_mfma_f32_32x32x16_bf16 v[50:65], v[238:241], v[222:225], v[50:65]
	v_mfma_f32_32x32x16_bf16 v[2:17], v[238:241], v[230:233], v[2:17]
	s_waitcnt lgkmcnt(1)
	v_mfma_f32_32x32x16_bf16 v[66:81], v[194:197], v[214:217], v[66:81]
	v_mfma_f32_32x32x16_bf16 v[34:49], v[194:197], v[222:225], v[34:49]
	v_mfma_f32_32x32x16_bf16 v[18:33], v[194:197], v[230:233], v[18:33]
	s_setprio 0
	ds_read_b128 v[214:217], v98 offset:36928
	ds_read_b128 v[222:225], v98 offset:41536
	ds_read_b128 v[230:233], v98 offset:46144
	ds_read_b128 v[238:241], v101 offset:64
	ds_read_b128 v[194:197], v101 offset:4672
	s_setprio 1
	v_mfma_f32_32x32x16_bf16 v[82:97], v[190:193], v[218:221], v[82:97]
	v_mfma_f32_32x32x16_bf16 v[50:65], v[190:193], v[226:229], v[50:65]
	v_mfma_f32_32x32x16_bf16 v[2:17], v[190:193], v[234:237], v[2:17]
	s_waitcnt lgkmcnt(5)
	v_mfma_f32_32x32x16_bf16 v[66:81], v[198:201], v[218:221], v[66:81]
	v_mfma_f32_32x32x16_bf16 v[34:49], v[198:201], v[226:229], v[34:49]
	v_mfma_f32_32x32x16_bf16 v[18:33], v[198:201], v[234:237], v[18:33]
	s_setprio 0
	ds_read_b128 v[218:221], v98 offset:36960
	ds_read_b128 v[226:229], v98 offset:41568
	ds_read_b128 v[234:237], v98 offset:46176
	ds_read_b128 v[190:193], v101 offset:96
	ds_read_b128 v[198:201], v101 offset:4704
	s_setprio 1
	s_waitcnt lgkmcnt(6)
	v_mfma_f32_32x32x16_bf16 v[82:97], v[238:241], v[214:217], v[82:97]
	v_mfma_f32_32x32x16_bf16 v[50:65], v[238:241], v[222:225], v[50:65]
	v_mfma_f32_32x32x16_bf16 v[2:17], v[238:241], v[230:233], v[2:17]
	s_waitcnt lgkmcnt(5)
	v_mfma_f32_32x32x16_bf16 v[66:81], v[194:197], v[214:217], v[66:81]
	v_mfma_f32_32x32x16_bf16 v[34:49], v[194:197], v[222:225], v[34:49]
	v_mfma_f32_32x32x16_bf16 v[18:33], v[194:197], v[230:233], v[18:33]
	s_setprio 0
	s_setprio 1
	s_waitcnt lgkmcnt(1)
	v_mfma_f32_32x32x16_bf16 v[82:97], v[190:193], v[218:221], v[82:97]
	v_mfma_f32_32x32x16_bf16 v[50:65], v[190:193], v[226:229], v[50:65]
	v_mfma_f32_32x32x16_bf16 v[2:17], v[190:193], v[234:237], v[2:17]
	s_waitcnt lgkmcnt(0)
	v_mfma_f32_32x32x16_bf16 v[66:81], v[198:201], v[218:221], v[66:81]
	v_mfma_f32_32x32x16_bf16 v[34:49], v[198:201], v[226:229], v[34:49]
	v_mfma_f32_32x32x16_bf16 v[18:33], v[198:201], v[234:237], v[18:33]
	s_setprio 0
	s_barrier
	global_load_dwordx4 v[214:217], v[106:107], off offset:896
	global_load_dwordx4 v[218:221], v[108:109], off offset:896
	global_load_dwordx4 v[222:225], v[102:103], off offset:896
	global_load_dwordx4 v[226:229], v[104:105], off offset:896
	global_load_dwordx4 v[230:233], v[110:111], off offset:896
	global_load_dwordx4 v[234:237], v[112:113], off offset:896
	global_load_dwordx4 v[238:241], v[116:117], off offset:896
	s_waitcnt vmcnt(18)
	ds_write_b128 v119, v[140:143]
	ds_write_b128 v119, v[120:123] offset:9216
	ds_write_b128 v119, v[136:139] offset:18432
	s_waitcnt vmcnt(16)
	ds_write_b128 v119, v[148:151] offset:27648
	ds_write_b128 v119, v[144:147] offset:36864
	s_waitcnt vmcnt(15)
	ds_write_b128 v119, v[152:155] offset:46080
	s_waitcnt vmcnt(14)
	ds_write_b128 v119, v[156:159] offset:55296
	ds_read_b128 v[120:123], v115 offset:36864
	ds_read_b128 v[136:139], v115 offset:36896
	ds_read_b128 v[140:143], v115 offset:41472
	ds_read_b128 v[144:147], v115 offset:41504
	ds_read_b128 v[148:151], v115 offset:46080
	ds_read_b128 v[152:155], v115 offset:46112
	ds_read_b128 v[156:159], v100
	ds_read_b128 v[190:193], v100 offset:32
	ds_read_b128 v[194:197], v100 offset:4608
	ds_read_b128 v[198:201], v100 offset:4640
	s_setprio 1
	s_waitcnt lgkmcnt(3)
	v_mfma_f32_32x32x16_bf16 v[82:97], v[156:159], v[120:123], v[82:97]
	v_mfma_f32_32x32x16_bf16 v[50:65], v[156:159], v[140:143], v[50:65]
	v_mfma_f32_32x32x16_bf16 v[2:17], v[156:159], v[148:151], v[2:17]
	s_waitcnt lgkmcnt(1)
	v_mfma_f32_32x32x16_bf16 v[66:81], v[194:197], v[120:123], v[66:81]
	v_mfma_f32_32x32x16_bf16 v[34:49], v[194:197], v[140:143], v[34:49]
	v_mfma_f32_32x32x16_bf16 v[18:33], v[194:197], v[148:151], v[18:33]
	s_setprio 0
	ds_read_b128 v[120:123], v115 offset:36928
	ds_read_b128 v[140:143], v115 offset:41536
	ds_read_b128 v[148:151], v115 offset:46144
	ds_read_b128 v[156:159], v100 offset:64
	ds_read_b128 v[194:197], v100 offset:4672
	s_setprio 1
	v_mfma_f32_32x32x16_bf16 v[82:97], v[190:193], v[136:139], v[82:97]
	v_mfma_f32_32x32x16_bf16 v[50:65], v[190:193], v[144:147], v[50:65]
	v_mfma_f32_32x32x16_bf16 v[2:17], v[190:193], v[152:155], v[2:17]
	s_waitcnt lgkmcnt(5)
	v_mfma_f32_32x32x16_bf16 v[66:81], v[198:201], v[136:139], v[66:81]
	v_mfma_f32_32x32x16_bf16 v[34:49], v[198:201], v[144:147], v[34:49]
	v_mfma_f32_32x32x16_bf16 v[18:33], v[198:201], v[152:155], v[18:33]
	s_setprio 0
	ds_read_b128 v[136:139], v115 offset:36960
	ds_read_b128 v[144:147], v115 offset:41568
	ds_read_b128 v[152:155], v115 offset:46176
	ds_read_b128 v[190:193], v100 offset:96
	ds_read_b128 v[198:201], v100 offset:4704
	s_setprio 1
	s_waitcnt lgkmcnt(6)
	v_mfma_f32_32x32x16_bf16 v[82:97], v[156:159], v[120:123], v[82:97]
	v_mfma_f32_32x32x16_bf16 v[50:65], v[156:159], v[140:143], v[50:65]
	v_mfma_f32_32x32x16_bf16 v[2:17], v[156:159], v[148:151], v[2:17]
	s_waitcnt lgkmcnt(5)
	v_mfma_f32_32x32x16_bf16 v[66:81], v[194:197], v[120:123], v[66:81]
	v_mfma_f32_32x32x16_bf16 v[34:49], v[194:197], v[140:143], v[34:49]
	v_mfma_f32_32x32x16_bf16 v[18:33], v[194:197], v[148:151], v[18:33]
	s_setprio 0
	s_setprio 1
	s_waitcnt lgkmcnt(1)
	v_mfma_f32_32x32x16_bf16 v[82:97], v[190:193], v[136:139], v[82:97]
	v_mfma_f32_32x32x16_bf16 v[50:65], v[190:193], v[144:147], v[50:65]
	v_mfma_f32_32x32x16_bf16 v[2:17], v[190:193], v[152:155], v[2:17]
	s_waitcnt lgkmcnt(0)
	v_mfma_f32_32x32x16_bf16 v[66:81], v[198:201], v[136:139], v[66:81]
	v_mfma_f32_32x32x16_bf16 v[34:49], v[198:201], v[144:147], v[34:49]
	v_mfma_f32_32x32x16_bf16 v[18:33], v[198:201], v[152:155], v[18:33]
	s_setprio 0
	s_barrier
	global_load_dwordx4 v[120:123], v[106:107], off offset:1024
	global_load_dwordx4 v[136:139], v[108:109], off offset:1024
	global_load_dwordx4 v[140:143], v[102:103], off offset:1024
	global_load_dwordx4 v[144:147], v[104:105], off offset:1024
	global_load_dwordx4 v[148:151], v[110:111], off offset:1024
	global_load_dwordx4 v[152:155], v[112:113], off offset:1024
	global_load_dwordx4 v[156:159], v[116:117], off offset:1024
	s_waitcnt vmcnt(18)
	ds_write_b128 v114, v[170:173]
	ds_write_b128 v114, v[162:165] offset:9216
	ds_write_b128 v114, v[166:169] offset:18432
	s_waitcnt vmcnt(16)
	ds_write_b128 v114, v[178:181] offset:27648
	ds_write_b128 v114, v[174:177] offset:36864
	s_waitcnt vmcnt(15)
	ds_write_b128 v114, v[182:185] offset:46080
	s_waitcnt vmcnt(14)
	ds_write_b128 v114, v[186:189] offset:55296
	ds_read_b128 v[162:165], v98 offset:36864
	ds_read_b128 v[166:169], v98 offset:36896
	ds_read_b128 v[170:173], v98 offset:41472
	ds_read_b128 v[174:177], v98 offset:41504
	ds_read_b128 v[178:181], v98 offset:46080
	ds_read_b128 v[182:185], v98 offset:46112
	ds_read_b128 v[186:189], v101
	ds_read_b128 v[190:193], v101 offset:32
	ds_read_b128 v[194:197], v101 offset:4608
	ds_read_b128 v[198:201], v101 offset:4640
	s_setprio 1
	s_waitcnt lgkmcnt(3)
	v_mfma_f32_32x32x16_bf16 v[82:97], v[186:189], v[162:165], v[82:97]
	v_mfma_f32_32x32x16_bf16 v[50:65], v[186:189], v[170:173], v[50:65]
	v_mfma_f32_32x32x16_bf16 v[2:17], v[186:189], v[178:181], v[2:17]
	s_waitcnt lgkmcnt(1)
	v_mfma_f32_32x32x16_bf16 v[66:81], v[194:197], v[162:165], v[66:81]
	v_mfma_f32_32x32x16_bf16 v[34:49], v[194:197], v[170:173], v[34:49]
	v_mfma_f32_32x32x16_bf16 v[18:33], v[194:197], v[178:181], v[18:33]
	s_setprio 0
	ds_read_b128 v[162:165], v98 offset:36928
	ds_read_b128 v[170:173], v98 offset:41536
	ds_read_b128 v[178:181], v98 offset:46144
	ds_read_b128 v[186:189], v101 offset:64
	ds_read_b128 v[194:197], v101 offset:4672
	s_setprio 1
	v_mfma_f32_32x32x16_bf16 v[82:97], v[190:193], v[166:169], v[82:97]
	v_mfma_f32_32x32x16_bf16 v[50:65], v[190:193], v[174:177], v[50:65]
	v_mfma_f32_32x32x16_bf16 v[2:17], v[190:193], v[182:185], v[2:17]
	s_waitcnt lgkmcnt(5)
	v_mfma_f32_32x32x16_bf16 v[66:81], v[198:201], v[166:169], v[66:81]
	v_mfma_f32_32x32x16_bf16 v[34:49], v[198:201], v[174:177], v[34:49]
	v_mfma_f32_32x32x16_bf16 v[18:33], v[198:201], v[182:185], v[18:33]
	s_setprio 0
	ds_read_b128 v[166:169], v98 offset:36960
	ds_read_b128 v[174:177], v98 offset:41568
	ds_read_b128 v[182:185], v98 offset:46176
	ds_read_b128 v[190:193], v101 offset:96
	ds_read_b128 v[198:201], v101 offset:4704
	s_setprio 1
	s_waitcnt lgkmcnt(6)
	v_mfma_f32_32x32x16_bf16 v[82:97], v[186:189], v[162:165], v[82:97]
	v_mfma_f32_32x32x16_bf16 v[50:65], v[186:189], v[170:173], v[50:65]
	v_mfma_f32_32x32x16_bf16 v[2:17], v[186:189], v[178:181], v[2:17]
	s_waitcnt lgkmcnt(5)
	v_mfma_f32_32x32x16_bf16 v[66:81], v[194:197], v[162:165], v[66:81]
	v_mfma_f32_32x32x16_bf16 v[34:49], v[194:197], v[170:173], v[34:49]
	v_mfma_f32_32x32x16_bf16 v[18:33], v[194:197], v[178:181], v[18:33]
	s_setprio 0
	s_setprio 1
	s_waitcnt lgkmcnt(1)
	v_mfma_f32_32x32x16_bf16 v[82:97], v[190:193], v[166:169], v[82:97]
	v_mfma_f32_32x32x16_bf16 v[50:65], v[190:193], v[174:177], v[50:65]
	v_mfma_f32_32x32x16_bf16 v[2:17], v[190:193], v[182:185], v[2:17]
	s_waitcnt lgkmcnt(0)
	v_mfma_f32_32x32x16_bf16 v[66:81], v[198:201], v[166:169], v[66:81]
	v_mfma_f32_32x32x16_bf16 v[34:49], v[198:201], v[174:177], v[34:49]
	v_mfma_f32_32x32x16_bf16 v[18:33], v[198:201], v[182:185], v[18:33]
	s_setprio 0
	s_barrier
	global_load_dwordx4 v[162:165], v[106:107], off offset:1152
	global_load_dwordx4 v[166:169], v[108:109], off offset:1152
	global_load_dwordx4 v[170:173], v[102:103], off offset:1152
	global_load_dwordx4 v[174:177], v[104:105], off offset:1152
	global_load_dwordx4 v[178:181], v[110:111], off offset:1152
	global_load_dwordx4 v[182:185], v[112:113], off offset:1152
	global_load_dwordx4 v[186:189], v[116:117], off offset:1152
	s_waitcnt vmcnt(18)
	ds_write_b128 v119, v[222:225]
	ds_write_b128 v119, v[214:217] offset:9216
	ds_write_b128 v119, v[218:221] offset:18432
	s_waitcnt vmcnt(16)
	ds_write_b128 v119, v[230:233] offset:27648
	ds_write_b128 v119, v[226:229] offset:36864
	s_waitcnt vmcnt(15)
	ds_write_b128 v119, v[234:237] offset:46080
	s_waitcnt vmcnt(14)
	ds_write_b128 v119, v[238:241] offset:55296
	ds_read_b128 v[214:217], v115 offset:36864
	ds_read_b128 v[218:221], v115 offset:36896
	ds_read_b128 v[222:225], v115 offset:41472
	ds_read_b128 v[226:229], v115 offset:41504
	ds_read_b128 v[230:233], v115 offset:46080
	ds_read_b128 v[234:237], v115 offset:46112
	ds_read_b128 v[238:241], v100
	ds_read_b128 v[190:193], v100 offset:32
	ds_read_b128 v[194:197], v100 offset:4608
	ds_read_b128 v[198:201], v100 offset:4640
	s_setprio 1
	s_waitcnt lgkmcnt(3)
	v_mfma_f32_32x32x16_bf16 v[82:97], v[238:241], v[214:217], v[82:97]
	v_mfma_f32_32x32x16_bf16 v[50:65], v[238:241], v[222:225], v[50:65]
	v_mfma_f32_32x32x16_bf16 v[2:17], v[238:241], v[230:233], v[2:17]
	s_waitcnt lgkmcnt(1)
	v_mfma_f32_32x32x16_bf16 v[66:81], v[194:197], v[214:217], v[66:81]
	v_mfma_f32_32x32x16_bf16 v[34:49], v[194:197], v[222:225], v[34:49]
	v_mfma_f32_32x32x16_bf16 v[18:33], v[194:197], v[230:233], v[18:33]
	s_setprio 0
	ds_read_b128 v[214:217], v115 offset:36928
	ds_read_b128 v[222:225], v115 offset:41536
	ds_read_b128 v[230:233], v115 offset:46144
	ds_read_b128 v[238:241], v100 offset:64
	ds_read_b128 v[194:197], v100 offset:4672
	s_setprio 1
	v_mfma_f32_32x32x16_bf16 v[82:97], v[190:193], v[218:221], v[82:97]
	v_mfma_f32_32x32x16_bf16 v[50:65], v[190:193], v[226:229], v[50:65]
	v_mfma_f32_32x32x16_bf16 v[2:17], v[190:193], v[234:237], v[2:17]
	s_waitcnt lgkmcnt(5)
	v_mfma_f32_32x32x16_bf16 v[66:81], v[198:201], v[218:221], v[66:81]
	v_mfma_f32_32x32x16_bf16 v[34:49], v[198:201], v[226:229], v[34:49]
	v_mfma_f32_32x32x16_bf16 v[18:33], v[198:201], v[234:237], v[18:33]
	s_setprio 0
	ds_read_b128 v[218:221], v115 offset:36960
	ds_read_b128 v[226:229], v115 offset:41568
	ds_read_b128 v[234:237], v115 offset:46176
	ds_read_b128 v[190:193], v100 offset:96
	ds_read_b128 v[198:201], v100 offset:4704
	s_setprio 1
	s_waitcnt lgkmcnt(6)
	v_mfma_f32_32x32x16_bf16 v[82:97], v[238:241], v[214:217], v[82:97]
	v_mfma_f32_32x32x16_bf16 v[50:65], v[238:241], v[222:225], v[50:65]
	v_mfma_f32_32x32x16_bf16 v[2:17], v[238:241], v[230:233], v[2:17]
	s_waitcnt lgkmcnt(5)
	v_mfma_f32_32x32x16_bf16 v[66:81], v[194:197], v[214:217], v[66:81]
	v_mfma_f32_32x32x16_bf16 v[34:49], v[194:197], v[222:225], v[34:49]
	v_mfma_f32_32x32x16_bf16 v[18:33], v[194:197], v[230:233], v[18:33]
	s_setprio 0
	s_setprio 1
	s_waitcnt lgkmcnt(1)
	v_mfma_f32_32x32x16_bf16 v[82:97], v[190:193], v[218:221], v[82:97]
	v_mfma_f32_32x32x16_bf16 v[50:65], v[190:193], v[226:229], v[50:65]
	v_mfma_f32_32x32x16_bf16 v[2:17], v[190:193], v[234:237], v[2:17]
	s_waitcnt lgkmcnt(0)
	v_mfma_f32_32x32x16_bf16 v[66:81], v[198:201], v[218:221], v[66:81]
	v_mfma_f32_32x32x16_bf16 v[34:49], v[198:201], v[226:229], v[34:49]
	v_mfma_f32_32x32x16_bf16 v[18:33], v[198:201], v[234:237], v[18:33]
	s_setprio 0
	s_barrier
	global_load_dwordx4 v[214:217], v[106:107], off offset:1280
	global_load_dwordx4 v[218:221], v[108:109], off offset:1280
	global_load_dwordx4 v[222:225], v[102:103], off offset:1280
	global_load_dwordx4 v[226:229], v[104:105], off offset:1280
	global_load_dwordx4 v[230:233], v[110:111], off offset:1280
	global_load_dwordx4 v[234:237], v[112:113], off offset:1280
	global_load_dwordx4 v[238:241], v[116:117], off offset:1280
	s_waitcnt vmcnt(18)
	ds_write_b128 v114, v[140:143]
	ds_write_b128 v114, v[120:123] offset:9216
	ds_write_b128 v114, v[136:139] offset:18432
	s_waitcnt vmcnt(16)
	ds_write_b128 v114, v[148:151] offset:27648
	ds_write_b128 v114, v[144:147] offset:36864
	s_waitcnt vmcnt(15)
	ds_write_b128 v114, v[152:155] offset:46080
	s_waitcnt vmcnt(14)
	ds_write_b128 v114, v[156:159] offset:55296
	ds_read_b128 v[120:123], v98 offset:36864
	ds_read_b128 v[136:139], v98 offset:36896
	ds_read_b128 v[140:143], v98 offset:41472
	ds_read_b128 v[144:147], v98 offset:41504
	ds_read_b128 v[148:151], v98 offset:46080
	ds_read_b128 v[152:155], v98 offset:46112
	ds_read_b128 v[156:159], v101
	ds_read_b128 v[190:193], v101 offset:32
	ds_read_b128 v[194:197], v101 offset:4608
	ds_read_b128 v[198:201], v101 offset:4640
	s_setprio 1
	s_waitcnt lgkmcnt(3)
	v_mfma_f32_32x32x16_bf16 v[82:97], v[156:159], v[120:123], v[82:97]
	v_mfma_f32_32x32x16_bf16 v[50:65], v[156:159], v[140:143], v[50:65]
	v_mfma_f32_32x32x16_bf16 v[2:17], v[156:159], v[148:151], v[2:17]
	s_waitcnt lgkmcnt(1)
	v_mfma_f32_32x32x16_bf16 v[66:81], v[194:197], v[120:123], v[66:81]
	v_mfma_f32_32x32x16_bf16 v[34:49], v[194:197], v[140:143], v[34:49]
	v_mfma_f32_32x32x16_bf16 v[18:33], v[194:197], v[148:151], v[18:33]
	s_setprio 0
	ds_read_b128 v[120:123], v98 offset:36928
	ds_read_b128 v[140:143], v98 offset:41536
	ds_read_b128 v[148:151], v98 offset:46144
	ds_read_b128 v[156:159], v101 offset:64
	ds_read_b128 v[194:197], v101 offset:4672
	s_setprio 1
	v_mfma_f32_32x32x16_bf16 v[82:97], v[190:193], v[136:139], v[82:97]
	v_mfma_f32_32x32x16_bf16 v[50:65], v[190:193], v[144:147], v[50:65]
	v_mfma_f32_32x32x16_bf16 v[2:17], v[190:193], v[152:155], v[2:17]
	s_waitcnt lgkmcnt(5)
	v_mfma_f32_32x32x16_bf16 v[66:81], v[198:201], v[136:139], v[66:81]
	v_mfma_f32_32x32x16_bf16 v[34:49], v[198:201], v[144:147], v[34:49]
	v_mfma_f32_32x32x16_bf16 v[18:33], v[198:201], v[152:155], v[18:33]
	s_setprio 0
	ds_read_b128 v[136:139], v98 offset:36960
	ds_read_b128 v[144:147], v98 offset:41568
	ds_read_b128 v[152:155], v98 offset:46176
	ds_read_b128 v[190:193], v101 offset:96
	ds_read_b128 v[198:201], v101 offset:4704
	s_setprio 1
	s_waitcnt lgkmcnt(6)
	v_mfma_f32_32x32x16_bf16 v[82:97], v[156:159], v[120:123], v[82:97]
	v_mfma_f32_32x32x16_bf16 v[50:65], v[156:159], v[140:143], v[50:65]
	v_mfma_f32_32x32x16_bf16 v[2:17], v[156:159], v[148:151], v[2:17]
	s_waitcnt lgkmcnt(5)
	v_mfma_f32_32x32x16_bf16 v[66:81], v[194:197], v[120:123], v[66:81]
	v_mfma_f32_32x32x16_bf16 v[34:49], v[194:197], v[140:143], v[34:49]
	v_mfma_f32_32x32x16_bf16 v[18:33], v[194:197], v[148:151], v[18:33]
	s_setprio 0
	s_setprio 1
	s_waitcnt lgkmcnt(1)
	v_mfma_f32_32x32x16_bf16 v[82:97], v[190:193], v[136:139], v[82:97]
	v_mfma_f32_32x32x16_bf16 v[50:65], v[190:193], v[144:147], v[50:65]
	v_mfma_f32_32x32x16_bf16 v[2:17], v[190:193], v[152:155], v[2:17]
	s_waitcnt lgkmcnt(0)
	v_mfma_f32_32x32x16_bf16 v[66:81], v[198:201], v[136:139], v[66:81]
	v_mfma_f32_32x32x16_bf16 v[34:49], v[198:201], v[144:147], v[34:49]
	v_mfma_f32_32x32x16_bf16 v[18:33], v[198:201], v[152:155], v[18:33]
	s_setprio 0
	s_barrier
	global_load_dwordx4 v[120:123], v[106:107], off offset:1408
	global_load_dwordx4 v[136:139], v[108:109], off offset:1408
	global_load_dwordx4 v[140:143], v[102:103], off offset:1408
	global_load_dwordx4 v[144:147], v[104:105], off offset:1408
	global_load_dwordx4 v[148:151], v[110:111], off offset:1408
	global_load_dwordx4 v[152:155], v[112:113], off offset:1408
	global_load_dwordx4 v[156:159], v[116:117], off offset:1408
	s_waitcnt vmcnt(18)
	ds_write_b128 v119, v[170:173]
	ds_write_b128 v119, v[162:165] offset:9216
	ds_write_b128 v119, v[166:169] offset:18432
	s_waitcnt vmcnt(16)
	ds_write_b128 v119, v[178:181] offset:27648
	ds_write_b128 v119, v[174:177] offset:36864
	s_waitcnt vmcnt(15)
	ds_write_b128 v119, v[182:185] offset:46080
	s_waitcnt vmcnt(14)
	ds_write_b128 v119, v[186:189] offset:55296
	ds_read_b128 v[162:165], v115 offset:36864
	ds_read_b128 v[166:169], v115 offset:36896
	ds_read_b128 v[170:173], v115 offset:41472
	ds_read_b128 v[174:177], v115 offset:41504
	ds_read_b128 v[178:181], v115 offset:46080
	ds_read_b128 v[182:185], v115 offset:46112
	ds_read_b128 v[186:189], v100
	ds_read_b128 v[190:193], v100 offset:32
	ds_read_b128 v[194:197], v100 offset:4608
	ds_read_b128 v[198:201], v100 offset:4640
	s_setprio 1
	s_waitcnt lgkmcnt(3)
	v_mfma_f32_32x32x16_bf16 v[82:97], v[186:189], v[162:165], v[82:97]
	v_mfma_f32_32x32x16_bf16 v[50:65], v[186:189], v[170:173], v[50:65]
	v_mfma_f32_32x32x16_bf16 v[2:17], v[186:189], v[178:181], v[2:17]
	s_waitcnt lgkmcnt(1)
	v_mfma_f32_32x32x16_bf16 v[66:81], v[194:197], v[162:165], v[66:81]
	v_mfma_f32_32x32x16_bf16 v[34:49], v[194:197], v[170:173], v[34:49]
	v_mfma_f32_32x32x16_bf16 v[18:33], v[194:197], v[178:181], v[18:33]
	s_setprio 0
	ds_read_b128 v[162:165], v115 offset:36928
	ds_read_b128 v[170:173], v115 offset:41536
	ds_read_b128 v[178:181], v115 offset:46144
	ds_read_b128 v[186:189], v100 offset:64
	ds_read_b128 v[194:197], v100 offset:4672
	s_setprio 1
	v_mfma_f32_32x32x16_bf16 v[82:97], v[190:193], v[166:169], v[82:97]
	v_mfma_f32_32x32x16_bf16 v[50:65], v[190:193], v[174:177], v[50:65]
	v_mfma_f32_32x32x16_bf16 v[2:17], v[190:193], v[182:185], v[2:17]
	s_waitcnt lgkmcnt(5)
	v_mfma_f32_32x32x16_bf16 v[66:81], v[198:201], v[166:169], v[66:81]
	v_mfma_f32_32x32x16_bf16 v[34:49], v[198:201], v[174:177], v[34:49]
	v_mfma_f32_32x32x16_bf16 v[18:33], v[198:201], v[182:185], v[18:33]
	s_setprio 0
	ds_read_b128 v[166:169], v115 offset:36960
	ds_read_b128 v[174:177], v115 offset:41568
	ds_read_b128 v[182:185], v115 offset:46176
	ds_read_b128 v[190:193], v100 offset:96
	ds_read_b128 v[198:201], v100 offset:4704
	s_setprio 1
	s_waitcnt lgkmcnt(6)
	v_mfma_f32_32x32x16_bf16 v[82:97], v[186:189], v[162:165], v[82:97]
	v_mfma_f32_32x32x16_bf16 v[50:65], v[186:189], v[170:173], v[50:65]
	v_mfma_f32_32x32x16_bf16 v[2:17], v[186:189], v[178:181], v[2:17]
	s_waitcnt lgkmcnt(5)
	v_mfma_f32_32x32x16_bf16 v[66:81], v[194:197], v[162:165], v[66:81]
	v_mfma_f32_32x32x16_bf16 v[34:49], v[194:197], v[170:173], v[34:49]
	v_mfma_f32_32x32x16_bf16 v[18:33], v[194:197], v[178:181], v[18:33]
	s_setprio 0
	s_setprio 1
	s_waitcnt lgkmcnt(1)
	v_mfma_f32_32x32x16_bf16 v[82:97], v[190:193], v[166:169], v[82:97]
	v_mfma_f32_32x32x16_bf16 v[50:65], v[190:193], v[174:177], v[50:65]
	v_mfma_f32_32x32x16_bf16 v[2:17], v[190:193], v[182:185], v[2:17]
	s_waitcnt lgkmcnt(0)
	v_mfma_f32_32x32x16_bf16 v[66:81], v[198:201], v[166:169], v[66:81]
	v_mfma_f32_32x32x16_bf16 v[34:49], v[198:201], v[174:177], v[34:49]
	v_mfma_f32_32x32x16_bf16 v[18:33], v[198:201], v[182:185], v[18:33]
	s_setprio 0
	s_barrier
	global_load_dwordx4 v[162:165], v[106:107], off offset:1536
	global_load_dwordx4 v[166:169], v[108:109], off offset:1536
	global_load_dwordx4 v[170:173], v[102:103], off offset:1536
	global_load_dwordx4 v[174:177], v[104:105], off offset:1536
	global_load_dwordx4 v[178:181], v[110:111], off offset:1536
	global_load_dwordx4 v[182:185], v[112:113], off offset:1536
	global_load_dwordx4 v[186:189], v[116:117], off offset:1536
	s_waitcnt vmcnt(18)
	ds_write_b128 v114, v[222:225]
	ds_write_b128 v114, v[214:217] offset:9216
	ds_write_b128 v114, v[218:221] offset:18432
	s_waitcnt vmcnt(16)
	ds_write_b128 v114, v[230:233] offset:27648
	ds_write_b128 v114, v[226:229] offset:36864
	s_waitcnt vmcnt(15)
	ds_write_b128 v114, v[234:237] offset:46080
	s_waitcnt vmcnt(14)
	ds_write_b128 v114, v[238:241] offset:55296
	ds_read_b128 v[214:217], v98 offset:36864
	ds_read_b128 v[218:221], v98 offset:36896
	ds_read_b128 v[222:225], v98 offset:41472
	ds_read_b128 v[226:229], v98 offset:41504
	ds_read_b128 v[230:233], v98 offset:46080
	ds_read_b128 v[234:237], v98 offset:46112
	ds_read_b128 v[238:241], v101
	ds_read_b128 v[190:193], v101 offset:32
	ds_read_b128 v[194:197], v101 offset:4608
	ds_read_b128 v[198:201], v101 offset:4640
	s_setprio 1
	s_waitcnt lgkmcnt(3)
	v_mfma_f32_32x32x16_bf16 v[82:97], v[238:241], v[214:217], v[82:97]
	v_mfma_f32_32x32x16_bf16 v[50:65], v[238:241], v[222:225], v[50:65]
	v_mfma_f32_32x32x16_bf16 v[2:17], v[238:241], v[230:233], v[2:17]
	s_waitcnt lgkmcnt(1)
	v_mfma_f32_32x32x16_bf16 v[66:81], v[194:197], v[214:217], v[66:81]
	v_mfma_f32_32x32x16_bf16 v[34:49], v[194:197], v[222:225], v[34:49]
	v_mfma_f32_32x32x16_bf16 v[18:33], v[194:197], v[230:233], v[18:33]
	s_setprio 0
	ds_read_b128 v[214:217], v98 offset:36928
	ds_read_b128 v[222:225], v98 offset:41536
	ds_read_b128 v[230:233], v98 offset:46144
	ds_read_b128 v[238:241], v101 offset:64
	ds_read_b128 v[194:197], v101 offset:4672
	s_setprio 1
	v_mfma_f32_32x32x16_bf16 v[82:97], v[190:193], v[218:221], v[82:97]
	v_mfma_f32_32x32x16_bf16 v[50:65], v[190:193], v[226:229], v[50:65]
	v_mfma_f32_32x32x16_bf16 v[2:17], v[190:193], v[234:237], v[2:17]
	s_waitcnt lgkmcnt(5)
	v_mfma_f32_32x32x16_bf16 v[66:81], v[198:201], v[218:221], v[66:81]
	v_mfma_f32_32x32x16_bf16 v[34:49], v[198:201], v[226:229], v[34:49]
	v_mfma_f32_32x32x16_bf16 v[18:33], v[198:201], v[234:237], v[18:33]
	s_setprio 0
	ds_read_b128 v[218:221], v98 offset:36960
	ds_read_b128 v[226:229], v98 offset:41568
	ds_read_b128 v[234:237], v98 offset:46176
	ds_read_b128 v[190:193], v101 offset:96
	ds_read_b128 v[198:201], v101 offset:4704
	s_setprio 1
	s_waitcnt lgkmcnt(6)
	v_mfma_f32_32x32x16_bf16 v[82:97], v[238:241], v[214:217], v[82:97]
	v_mfma_f32_32x32x16_bf16 v[50:65], v[238:241], v[222:225], v[50:65]
	v_mfma_f32_32x32x16_bf16 v[2:17], v[238:241], v[230:233], v[2:17]
	s_waitcnt lgkmcnt(5)
	v_mfma_f32_32x32x16_bf16 v[66:81], v[194:197], v[214:217], v[66:81]
	v_mfma_f32_32x32x16_bf16 v[34:49], v[194:197], v[222:225], v[34:49]
	v_mfma_f32_32x32x16_bf16 v[18:33], v[194:197], v[230:233], v[18:33]
	s_setprio 0
	s_setprio 1
	s_waitcnt lgkmcnt(1)
	v_mfma_f32_32x32x16_bf16 v[82:97], v[190:193], v[218:221], v[82:97]
	v_mfma_f32_32x32x16_bf16 v[50:65], v[190:193], v[226:229], v[50:65]
	v_mfma_f32_32x32x16_bf16 v[2:17], v[190:193], v[234:237], v[2:17]
	s_waitcnt lgkmcnt(0)
	v_mfma_f32_32x32x16_bf16 v[66:81], v[198:201], v[218:221], v[66:81]
	v_mfma_f32_32x32x16_bf16 v[34:49], v[198:201], v[226:229], v[34:49]
	v_mfma_f32_32x32x16_bf16 v[18:33], v[198:201], v[234:237], v[18:33]
	s_setprio 0
	s_barrier
	global_load_dwordx4 v[214:217], v[106:107], off offset:1664
	global_load_dwordx4 v[218:221], v[108:109], off offset:1664
	global_load_dwordx4 v[222:225], v[102:103], off offset:1664
	global_load_dwordx4 v[226:229], v[104:105], off offset:1664
	global_load_dwordx4 v[230:233], v[110:111], off offset:1664
	global_load_dwordx4 v[234:237], v[112:113], off offset:1664
	global_load_dwordx4 v[238:241], v[116:117], off offset:1664
	s_waitcnt vmcnt(18)
	ds_write_b128 v119, v[140:143]
	ds_write_b128 v119, v[120:123] offset:9216
	ds_write_b128 v119, v[136:139] offset:18432
	s_waitcnt vmcnt(16)
	ds_write_b128 v119, v[148:151] offset:27648
	ds_write_b128 v119, v[144:147] offset:36864
	s_waitcnt vmcnt(15)
	ds_write_b128 v119, v[152:155] offset:46080
	s_waitcnt vmcnt(14)
	ds_write_b128 v119, v[156:159] offset:55296
	ds_read_b128 v[120:123], v115 offset:36864
	ds_read_b128 v[136:139], v115 offset:36896
	ds_read_b128 v[140:143], v115 offset:41472
	ds_read_b128 v[144:147], v115 offset:41504
	ds_read_b128 v[148:151], v115 offset:46080
	ds_read_b128 v[152:155], v115 offset:46112
	ds_read_b128 v[156:159], v100
	ds_read_b128 v[190:193], v100 offset:32
	ds_read_b128 v[194:197], v100 offset:4608
	ds_read_b128 v[198:201], v100 offset:4640
	s_setprio 1
	s_waitcnt lgkmcnt(3)
	v_mfma_f32_32x32x16_bf16 v[82:97], v[156:159], v[120:123], v[82:97]
	v_mfma_f32_32x32x16_bf16 v[50:65], v[156:159], v[140:143], v[50:65]
	v_mfma_f32_32x32x16_bf16 v[2:17], v[156:159], v[148:151], v[2:17]
	s_waitcnt lgkmcnt(1)
	v_mfma_f32_32x32x16_bf16 v[66:81], v[194:197], v[120:123], v[66:81]
	v_mfma_f32_32x32x16_bf16 v[34:49], v[194:197], v[140:143], v[34:49]
	v_mfma_f32_32x32x16_bf16 v[18:33], v[194:197], v[148:151], v[18:33]
	s_setprio 0
	ds_read_b128 v[120:123], v115 offset:36928
	ds_read_b128 v[140:143], v115 offset:41536
	ds_read_b128 v[148:151], v115 offset:46144
	ds_read_b128 v[156:159], v100 offset:64
	ds_read_b128 v[194:197], v100 offset:4672
	s_setprio 1
	v_mfma_f32_32x32x16_bf16 v[82:97], v[190:193], v[136:139], v[82:97]
	v_mfma_f32_32x32x16_bf16 v[50:65], v[190:193], v[144:147], v[50:65]
	v_mfma_f32_32x32x16_bf16 v[2:17], v[190:193], v[152:155], v[2:17]
	s_waitcnt lgkmcnt(5)
	v_mfma_f32_32x32x16_bf16 v[66:81], v[198:201], v[136:139], v[66:81]
	v_mfma_f32_32x32x16_bf16 v[34:49], v[198:201], v[144:147], v[34:49]
	v_mfma_f32_32x32x16_bf16 v[18:33], v[198:201], v[152:155], v[18:33]
	s_setprio 0
	ds_read_b128 v[136:139], v115 offset:36960
	ds_read_b128 v[144:147], v115 offset:41568
	ds_read_b128 v[152:155], v115 offset:46176
	ds_read_b128 v[190:193], v100 offset:96
	ds_read_b128 v[198:201], v100 offset:4704
	s_setprio 1
	s_waitcnt lgkmcnt(6)
	v_mfma_f32_32x32x16_bf16 v[82:97], v[156:159], v[120:123], v[82:97]
	v_mfma_f32_32x32x16_bf16 v[50:65], v[156:159], v[140:143], v[50:65]
	v_mfma_f32_32x32x16_bf16 v[2:17], v[156:159], v[148:151], v[2:17]
	s_waitcnt lgkmcnt(5)
	v_mfma_f32_32x32x16_bf16 v[66:81], v[194:197], v[120:123], v[66:81]
	v_mfma_f32_32x32x16_bf16 v[34:49], v[194:197], v[140:143], v[34:49]
	v_mfma_f32_32x32x16_bf16 v[18:33], v[194:197], v[148:151], v[18:33]
	s_setprio 0
	s_setprio 1
	s_waitcnt lgkmcnt(1)
	v_mfma_f32_32x32x16_bf16 v[82:97], v[190:193], v[136:139], v[82:97]
	v_mfma_f32_32x32x16_bf16 v[50:65], v[190:193], v[144:147], v[50:65]
	v_mfma_f32_32x32x16_bf16 v[2:17], v[190:193], v[152:155], v[2:17]
	s_waitcnt lgkmcnt(0)
	v_mfma_f32_32x32x16_bf16 v[66:81], v[198:201], v[136:139], v[66:81]
	v_mfma_f32_32x32x16_bf16 v[34:49], v[198:201], v[144:147], v[34:49]
	v_mfma_f32_32x32x16_bf16 v[18:33], v[198:201], v[152:155], v[18:33]
	s_setprio 0
	s_barrier
	global_load_dwordx4 v[120:123], v[106:107], off offset:1792
	global_load_dwordx4 v[136:139], v[108:109], off offset:1792
	global_load_dwordx4 v[140:143], v[102:103], off offset:1792
	global_load_dwordx4 v[144:147], v[104:105], off offset:1792
	global_load_dwordx4 v[148:151], v[110:111], off offset:1792
	global_load_dwordx4 v[152:155], v[112:113], off offset:1792
	global_load_dwordx4 v[156:159], v[116:117], off offset:1792
	s_waitcnt vmcnt(18)
	ds_write_b128 v114, v[170:173]
	ds_write_b128 v114, v[162:165] offset:9216
	ds_write_b128 v114, v[166:169] offset:18432
	s_waitcnt vmcnt(16)
	ds_write_b128 v114, v[178:181] offset:27648
	ds_write_b128 v114, v[174:177] offset:36864
	s_waitcnt vmcnt(15)
	ds_write_b128 v114, v[182:185] offset:46080
	s_waitcnt vmcnt(14)
	ds_write_b128 v114, v[186:189] offset:55296
	ds_read_b128 v[162:165], v98 offset:36864
	ds_read_b128 v[166:169], v98 offset:36896
	ds_read_b128 v[170:173], v98 offset:41472
	ds_read_b128 v[174:177], v98 offset:41504
	ds_read_b128 v[178:181], v98 offset:46080
	ds_read_b128 v[182:185], v98 offset:46112
	ds_read_b128 v[186:189], v101
	ds_read_b128 v[190:193], v101 offset:32
	ds_read_b128 v[194:197], v101 offset:4608
	ds_read_b128 v[198:201], v101 offset:4640
	s_setprio 1
	s_waitcnt lgkmcnt(3)
	v_mfma_f32_32x32x16_bf16 v[82:97], v[186:189], v[162:165], v[82:97]
	v_mfma_f32_32x32x16_bf16 v[50:65], v[186:189], v[170:173], v[50:65]
	v_mfma_f32_32x32x16_bf16 v[2:17], v[186:189], v[178:181], v[2:17]
	s_waitcnt lgkmcnt(1)
	v_mfma_f32_32x32x16_bf16 v[66:81], v[194:197], v[162:165], v[66:81]
	v_mfma_f32_32x32x16_bf16 v[34:49], v[194:197], v[170:173], v[34:49]
	v_mfma_f32_32x32x16_bf16 v[18:33], v[194:197], v[178:181], v[18:33]
	s_setprio 0
	ds_read_b128 v[162:165], v98 offset:36928
	ds_read_b128 v[170:173], v98 offset:41536
	ds_read_b128 v[178:181], v98 offset:46144
	ds_read_b128 v[186:189], v101 offset:64
	ds_read_b128 v[194:197], v101 offset:4672
	s_setprio 1
	v_mfma_f32_32x32x16_bf16 v[82:97], v[190:193], v[166:169], v[82:97]
	v_mfma_f32_32x32x16_bf16 v[50:65], v[190:193], v[174:177], v[50:65]
	v_mfma_f32_32x32x16_bf16 v[2:17], v[190:193], v[182:185], v[2:17]
	s_waitcnt lgkmcnt(5)
	v_mfma_f32_32x32x16_bf16 v[66:81], v[198:201], v[166:169], v[66:81]
	v_mfma_f32_32x32x16_bf16 v[34:49], v[198:201], v[174:177], v[34:49]
	v_mfma_f32_32x32x16_bf16 v[18:33], v[198:201], v[182:185], v[18:33]
	s_setprio 0
	ds_read_b128 v[166:169], v98 offset:36960
	ds_read_b128 v[174:177], v98 offset:41568
	ds_read_b128 v[182:185], v98 offset:46176
	ds_read_b128 v[190:193], v101 offset:96
	ds_read_b128 v[198:201], v101 offset:4704
	s_setprio 1
	s_waitcnt lgkmcnt(6)
	v_mfma_f32_32x32x16_bf16 v[82:97], v[186:189], v[162:165], v[82:97]
	v_mfma_f32_32x32x16_bf16 v[50:65], v[186:189], v[170:173], v[50:65]
	v_mfma_f32_32x32x16_bf16 v[2:17], v[186:189], v[178:181], v[2:17]
	s_waitcnt lgkmcnt(5)
	v_mfma_f32_32x32x16_bf16 v[66:81], v[194:197], v[162:165], v[66:81]
	v_mfma_f32_32x32x16_bf16 v[34:49], v[194:197], v[170:173], v[34:49]
	v_mfma_f32_32x32x16_bf16 v[18:33], v[194:197], v[178:181], v[18:33]
	s_setprio 0
	s_setprio 1
	s_waitcnt lgkmcnt(1)
	v_mfma_f32_32x32x16_bf16 v[82:97], v[190:193], v[166:169], v[82:97]
	v_mfma_f32_32x32x16_bf16 v[50:65], v[190:193], v[174:177], v[50:65]
	v_mfma_f32_32x32x16_bf16 v[2:17], v[190:193], v[182:185], v[2:17]
	s_waitcnt lgkmcnt(0)
	v_mfma_f32_32x32x16_bf16 v[66:81], v[198:201], v[166:169], v[66:81]
	v_mfma_f32_32x32x16_bf16 v[34:49], v[198:201], v[174:177], v[34:49]
	v_mfma_f32_32x32x16_bf16 v[18:33], v[198:201], v[182:185], v[18:33]
	s_setprio 0
	s_barrier
	global_load_dwordx4 v[162:165], v[106:107], off offset:1920
	global_load_dwordx4 v[166:169], v[108:109], off offset:1920
	global_load_dwordx4 v[170:173], v[102:103], off offset:1920
	global_load_dwordx4 v[174:177], v[104:105], off offset:1920
	global_load_dwordx4 v[178:181], v[110:111], off offset:1920
	global_load_dwordx4 v[182:185], v[112:113], off offset:1920
	global_load_dwordx4 v[186:189], v[116:117], off offset:1920
	s_waitcnt vmcnt(18)
	ds_write_b128 v119, v[222:225]
	ds_write_b128 v119, v[214:217] offset:9216
	ds_write_b128 v119, v[218:221] offset:18432
	s_waitcnt vmcnt(16)
	ds_write_b128 v119, v[230:233] offset:27648
	ds_write_b128 v119, v[226:229] offset:36864
	s_waitcnt vmcnt(15)
	ds_write_b128 v119, v[234:237] offset:46080
	s_waitcnt vmcnt(14)
	ds_write_b128 v119, v[238:241] offset:55296
	ds_read_b128 v[214:217], v115 offset:36864
	ds_read_b128 v[218:221], v115 offset:36896
	ds_read_b128 v[222:225], v115 offset:41472
	ds_read_b128 v[226:229], v115 offset:41504
	ds_read_b128 v[230:233], v115 offset:46080
	ds_read_b128 v[234:237], v115 offset:46112
	ds_read_b128 v[238:241], v100
	ds_read_b128 v[190:193], v100 offset:32
	ds_read_b128 v[194:197], v100 offset:4608
	ds_read_b128 v[198:201], v100 offset:4640
	s_setprio 1
	s_waitcnt lgkmcnt(3)
	v_mfma_f32_32x32x16_bf16 v[82:97], v[238:241], v[214:217], v[82:97]
	v_mfma_f32_32x32x16_bf16 v[50:65], v[238:241], v[222:225], v[50:65]
	v_mfma_f32_32x32x16_bf16 v[2:17], v[238:241], v[230:233], v[2:17]
	s_waitcnt lgkmcnt(1)
	v_mfma_f32_32x32x16_bf16 v[66:81], v[194:197], v[214:217], v[66:81]
	v_mfma_f32_32x32x16_bf16 v[34:49], v[194:197], v[222:225], v[34:49]
	v_mfma_f32_32x32x16_bf16 v[18:33], v[194:197], v[230:233], v[18:33]
	s_setprio 0
	ds_read_b128 v[214:217], v115 offset:36928
	ds_read_b128 v[222:225], v115 offset:41536
	ds_read_b128 v[230:233], v115 offset:46144
	ds_read_b128 v[238:241], v100 offset:64
	ds_read_b128 v[194:197], v100 offset:4672
	s_setprio 1
	v_mfma_f32_32x32x16_bf16 v[82:97], v[190:193], v[218:221], v[82:97]
	v_mfma_f32_32x32x16_bf16 v[50:65], v[190:193], v[226:229], v[50:65]
	v_mfma_f32_32x32x16_bf16 v[2:17], v[190:193], v[234:237], v[2:17]
	s_waitcnt lgkmcnt(5)
	v_mfma_f32_32x32x16_bf16 v[66:81], v[198:201], v[218:221], v[66:81]
	v_mfma_f32_32x32x16_bf16 v[34:49], v[198:201], v[226:229], v[34:49]
	v_mfma_f32_32x32x16_bf16 v[18:33], v[198:201], v[234:237], v[18:33]
	s_setprio 0
	ds_read_b128 v[218:221], v115 offset:36960
	ds_read_b128 v[226:229], v115 offset:41568
	ds_read_b128 v[234:237], v115 offset:46176
	ds_read_b128 v[190:193], v100 offset:96
	ds_read_b128 v[198:201], v100 offset:4704
	s_setprio 1
	s_waitcnt lgkmcnt(6)
	v_mfma_f32_32x32x16_bf16 v[82:97], v[238:241], v[214:217], v[82:97]
	v_mfma_f32_32x32x16_bf16 v[50:65], v[238:241], v[222:225], v[50:65]
	v_mfma_f32_32x32x16_bf16 v[2:17], v[238:241], v[230:233], v[2:17]
	s_waitcnt lgkmcnt(5)
	v_mfma_f32_32x32x16_bf16 v[66:81], v[194:197], v[214:217], v[66:81]
	v_mfma_f32_32x32x16_bf16 v[34:49], v[194:197], v[222:225], v[34:49]
	v_mfma_f32_32x32x16_bf16 v[18:33], v[194:197], v[230:233], v[18:33]
	s_setprio 0
	s_setprio 1
	s_waitcnt lgkmcnt(1)
	v_mfma_f32_32x32x16_bf16 v[82:97], v[190:193], v[218:221], v[82:97]
	v_mfma_f32_32x32x16_bf16 v[50:65], v[190:193], v[226:229], v[50:65]
	v_mfma_f32_32x32x16_bf16 v[2:17], v[190:193], v[234:237], v[2:17]
	s_waitcnt lgkmcnt(0)
	v_mfma_f32_32x32x16_bf16 v[66:81], v[198:201], v[218:221], v[66:81]
	v_mfma_f32_32x32x16_bf16 v[34:49], v[198:201], v[226:229], v[34:49]
	v_mfma_f32_32x32x16_bf16 v[18:33], v[198:201], v[234:237], v[18:33]
	s_setprio 0
	s_barrier
	s_waitcnt vmcnt(11)
	ds_write_b128 v114, v[140:143]
	ds_write_b128 v114, v[120:123] offset:9216
	ds_write_b128 v114, v[136:139] offset:18432
	s_waitcnt vmcnt(9)
	ds_write_b128 v114, v[148:151] offset:27648
	ds_write_b128 v114, v[144:147] offset:36864
	s_waitcnt vmcnt(8)
	ds_write_b128 v114, v[152:155] offset:46080
	s_waitcnt vmcnt(7)
	ds_write_b128 v114, v[156:159] offset:55296
	ds_read_b128 v[120:123], v98 offset:36864
	ds_read_b128 v[136:139], v98 offset:36896
	ds_read_b128 v[140:143], v98 offset:41472
	ds_read_b128 v[144:147], v98 offset:41504
	ds_read_b128 v[148:151], v98 offset:46080
	ds_read_b128 v[152:155], v98 offset:46112
	ds_read_b128 v[156:159], v101
	ds_read_b128 v[190:193], v101 offset:32
	ds_read_b128 v[194:197], v101 offset:4608
	ds_read_b128 v[198:201], v101 offset:4640
	s_setprio 1
	s_waitcnt lgkmcnt(3)
	v_mfma_f32_32x32x16_bf16 v[82:97], v[156:159], v[120:123], v[82:97]
	v_mfma_f32_32x32x16_bf16 v[50:65], v[156:159], v[140:143], v[50:65]
	v_mfma_f32_32x32x16_bf16 v[2:17], v[156:159], v[148:151], v[2:17]
	s_waitcnt lgkmcnt(1)
	v_mfma_f32_32x32x16_bf16 v[66:81], v[194:197], v[120:123], v[66:81]
	v_mfma_f32_32x32x16_bf16 v[34:49], v[194:197], v[140:143], v[34:49]
	v_mfma_f32_32x32x16_bf16 v[18:33], v[194:197], v[148:151], v[18:33]
	s_setprio 0
	ds_read_b128 v[120:123], v98 offset:36928
	ds_read_b128 v[140:143], v98 offset:41536
	ds_read_b128 v[148:151], v98 offset:46144
	ds_read_b128 v[156:159], v101 offset:64
	ds_read_b128 v[194:197], v101 offset:4672
	s_setprio 1
	v_mfma_f32_32x32x16_bf16 v[82:97], v[190:193], v[136:139], v[82:97]
	v_mfma_f32_32x32x16_bf16 v[50:65], v[190:193], v[144:147], v[50:65]
	v_mfma_f32_32x32x16_bf16 v[2:17], v[190:193], v[152:155], v[2:17]
	s_waitcnt lgkmcnt(5)
	v_mfma_f32_32x32x16_bf16 v[66:81], v[198:201], v[136:139], v[66:81]
	v_mfma_f32_32x32x16_bf16 v[34:49], v[198:201], v[144:147], v[34:49]
	v_mfma_f32_32x32x16_bf16 v[18:33], v[198:201], v[152:155], v[18:33]
	s_setprio 0
	ds_read_b128 v[136:139], v98 offset:36960
	ds_read_b128 v[144:147], v98 offset:41568
	ds_read_b128 v[152:155], v98 offset:46176
	ds_read_b128 v[190:193], v101 offset:96
	ds_read_b128 v[198:201], v101 offset:4704
	s_setprio 1
	s_waitcnt lgkmcnt(6)
	v_mfma_f32_32x32x16_bf16 v[82:97], v[156:159], v[120:123], v[82:97]
	v_mfma_f32_32x32x16_bf16 v[50:65], v[156:159], v[140:143], v[50:65]
	v_mfma_f32_32x32x16_bf16 v[2:17], v[156:159], v[148:151], v[2:17]
	s_waitcnt lgkmcnt(5)
	v_mfma_f32_32x32x16_bf16 v[66:81], v[194:197], v[120:123], v[66:81]
	v_mfma_f32_32x32x16_bf16 v[34:49], v[194:197], v[140:143], v[34:49]
	v_mfma_f32_32x32x16_bf16 v[18:33], v[194:197], v[148:151], v[18:33]
	s_setprio 0
	s_setprio 1
	s_waitcnt lgkmcnt(1)
	v_mfma_f32_32x32x16_bf16 v[82:97], v[190:193], v[136:139], v[82:97]
	v_mfma_f32_32x32x16_bf16 v[50:65], v[190:193], v[144:147], v[50:65]
	v_mfma_f32_32x32x16_bf16 v[2:17], v[190:193], v[152:155], v[2:17]
	s_waitcnt lgkmcnt(0)
	v_mfma_f32_32x32x16_bf16 v[66:81], v[198:201], v[136:139], v[66:81]
	v_mfma_f32_32x32x16_bf16 v[34:49], v[198:201], v[144:147], v[34:49]
	v_mfma_f32_32x32x16_bf16 v[18:33], v[198:201], v[152:155], v[18:33]
	s_setprio 0
	s_barrier
	s_waitcnt vmcnt(4)
	ds_write_b128 v119, v[170:173]
	ds_write_b128 v119, v[162:165] offset:9216
	ds_write_b128 v119, v[166:169] offset:18432
	s_waitcnt vmcnt(2)
	ds_write_b128 v119, v[178:181] offset:27648
	ds_write_b128 v119, v[174:177] offset:36864
	s_waitcnt vmcnt(1)
	ds_write_b128 v119, v[182:185] offset:46080
	s_waitcnt vmcnt(0)
	ds_write_b128 v119, v[186:189] offset:55296
	ds_read_b128 v[162:165], v115 offset:36864
	ds_read_b128 v[166:169], v115 offset:36896
	ds_read_b128 v[170:173], v115 offset:41472
	ds_read_b128 v[174:177], v115 offset:41504
	ds_read_b128 v[178:181], v115 offset:46080
	ds_read_b128 v[182:185], v115 offset:46112
	ds_read_b128 v[186:189], v100
	ds_read_b128 v[190:193], v100 offset:32
	ds_read_b128 v[194:197], v100 offset:4608
	ds_read_b128 v[198:201], v100 offset:4640
	s_setprio 1
	s_waitcnt lgkmcnt(3)
	v_mfma_f32_32x32x16_bf16 v[82:97], v[186:189], v[162:165], v[82:97]
	v_mfma_f32_32x32x16_bf16 v[50:65], v[186:189], v[170:173], v[50:65]
	v_mfma_f32_32x32x16_bf16 v[2:17], v[186:189], v[178:181], v[2:17]
	s_waitcnt lgkmcnt(1)
	v_mfma_f32_32x32x16_bf16 v[66:81], v[194:197], v[162:165], v[66:81]
	v_mfma_f32_32x32x16_bf16 v[34:49], v[194:197], v[170:173], v[34:49]
	v_mfma_f32_32x32x16_bf16 v[18:33], v[194:197], v[178:181], v[18:33]
	s_setprio 0
	ds_read_b128 v[162:165], v115 offset:36928
	ds_read_b128 v[170:173], v115 offset:41536
	ds_read_b128 v[178:181], v115 offset:46144
	ds_read_b128 v[186:189], v100 offset:64
	ds_read_b128 v[194:197], v100 offset:4672
	s_setprio 1
	v_mfma_f32_32x32x16_bf16 v[82:97], v[190:193], v[166:169], v[82:97]
	v_mfma_f32_32x32x16_bf16 v[50:65], v[190:193], v[174:177], v[50:65]
	v_mfma_f32_32x32x16_bf16 v[2:17], v[190:193], v[182:185], v[2:17]
	s_waitcnt lgkmcnt(5)
	v_mfma_f32_32x32x16_bf16 v[66:81], v[198:201], v[166:169], v[66:81]
	v_mfma_f32_32x32x16_bf16 v[34:49], v[198:201], v[174:177], v[34:49]
	v_mfma_f32_32x32x16_bf16 v[18:33], v[198:201], v[182:185], v[18:33]
	s_setprio 0
	ds_read_b128 v[166:169], v115 offset:36960
	ds_read_b128 v[174:177], v115 offset:41568
	ds_read_b128 v[182:185], v115 offset:46176
	ds_read_b128 v[190:193], v100 offset:96
	ds_read_b128 v[198:201], v100 offset:4704
	s_setprio 1
	s_waitcnt lgkmcnt(6)
	v_mfma_f32_32x32x16_bf16 v[82:97], v[186:189], v[162:165], v[82:97]
	v_mfma_f32_32x32x16_bf16 v[50:65], v[186:189], v[170:173], v[50:65]
	v_mfma_f32_32x32x16_bf16 v[2:17], v[186:189], v[178:181], v[2:17]
	s_waitcnt lgkmcnt(5)
	v_mfma_f32_32x32x16_bf16 v[66:81], v[194:197], v[162:165], v[66:81]
	v_mfma_f32_32x32x16_bf16 v[34:49], v[194:197], v[170:173], v[34:49]
	v_mfma_f32_32x32x16_bf16 v[18:33], v[194:197], v[178:181], v[18:33]
	s_setprio 0
	s_setprio 1
	s_waitcnt lgkmcnt(1)
	v_mfma_f32_32x32x16_bf16 v[82:97], v[190:193], v[166:169], v[82:97]
	v_mfma_f32_32x32x16_bf16 v[50:65], v[190:193], v[174:177], v[50:65]
	v_mfma_f32_32x32x16_bf16 v[2:17], v[190:193], v[182:185], v[2:17]
	s_waitcnt lgkmcnt(0)
	v_mfma_f32_32x32x16_bf16 v[66:81], v[198:201], v[166:169], v[66:81]
	v_mfma_f32_32x32x16_bf16 v[34:49], v[198:201], v[174:177], v[34:49]
	v_mfma_f32_32x32x16_bf16 v[18:33], v[198:201], v[182:185], v[18:33]
	s_setprio 0
	s_barrier
	ds_read_b128 v[214:217], v98 offset:36864
	ds_read_b128 v[218:221], v98 offset:36896
	ds_read_b128 v[222:225], v98 offset:41472
	ds_read_b128 v[226:229], v98 offset:41504
	ds_read_b128 v[230:233], v98 offset:46080
	ds_read_b128 v[234:237], v98 offset:46112
	ds_read_b128 v[238:241], v101
	ds_read_b128 v[190:193], v101 offset:32
	ds_read_b128 v[194:197], v101 offset:4608
	ds_read_b128 v[198:201], v101 offset:4640
	s_setprio 1
	s_waitcnt lgkmcnt(3)
	v_mfma_f32_32x32x16_bf16 v[82:97], v[238:241], v[214:217], v[82:97]
	v_mfma_f32_32x32x16_bf16 v[50:65], v[238:241], v[222:225], v[50:65]
	v_mfma_f32_32x32x16_bf16 v[2:17], v[238:241], v[230:233], v[2:17]
	s_waitcnt lgkmcnt(1)
	v_mfma_f32_32x32x16_bf16 v[66:81], v[194:197], v[214:217], v[66:81]
	v_mfma_f32_32x32x16_bf16 v[34:49], v[194:197], v[222:225], v[34:49]
	v_mfma_f32_32x32x16_bf16 v[18:33], v[194:197], v[230:233], v[18:33]
	s_setprio 0
	ds_read_b128 v[214:217], v98 offset:36928
	ds_read_b128 v[222:225], v98 offset:41536
	ds_read_b128 v[230:233], v98 offset:46144
	ds_read_b128 v[238:241], v101 offset:64
	ds_read_b128 v[194:197], v101 offset:4672
	s_setprio 1
	v_mfma_f32_32x32x16_bf16 v[82:97], v[190:193], v[218:221], v[82:97]
	v_mfma_f32_32x32x16_bf16 v[50:65], v[190:193], v[226:229], v[50:65]
	v_mfma_f32_32x32x16_bf16 v[2:17], v[190:193], v[234:237], v[2:17]
	s_waitcnt lgkmcnt(5)
	v_mfma_f32_32x32x16_bf16 v[66:81], v[198:201], v[218:221], v[66:81]
	v_mfma_f32_32x32x16_bf16 v[34:49], v[198:201], v[226:229], v[34:49]
	v_mfma_f32_32x32x16_bf16 v[18:33], v[198:201], v[234:237], v[18:33]
	s_setprio 0
	ds_read_b128 v[218:221], v98 offset:36960
	ds_read_b128 v[226:229], v98 offset:41568
	ds_read_b128 v[234:237], v98 offset:46176
	ds_read_b128 v[190:193], v101 offset:96
	ds_read_b128 v[198:201], v101 offset:4704
	s_setprio 1
	s_waitcnt lgkmcnt(6)
	v_mfma_f32_32x32x16_bf16 v[82:97], v[238:241], v[214:217], v[82:97]
	v_mfma_f32_32x32x16_bf16 v[50:65], v[238:241], v[222:225], v[50:65]
	v_mfma_f32_32x32x16_bf16 v[2:17], v[238:241], v[230:233], v[2:17]
	s_waitcnt lgkmcnt(5)
	v_mfma_f32_32x32x16_bf16 v[66:81], v[194:197], v[214:217], v[66:81]
	v_mfma_f32_32x32x16_bf16 v[34:49], v[194:197], v[222:225], v[34:49]
	v_mfma_f32_32x32x16_bf16 v[18:33], v[194:197], v[230:233], v[18:33]
	s_setprio 0
	s_setprio 1
	s_waitcnt lgkmcnt(1)
	v_mfma_f32_32x32x16_bf16 v[82:97], v[190:193], v[218:221], v[82:97]
	v_mfma_f32_32x32x16_bf16 v[50:65], v[190:193], v[226:229], v[50:65]
	v_mfma_f32_32x32x16_bf16 v[2:17], v[190:193], v[234:237], v[2:17]
	s_waitcnt lgkmcnt(0)
	v_mfma_f32_32x32x16_bf16 v[66:81], v[198:201], v[218:221], v[66:81]
	v_mfma_f32_32x32x16_bf16 v[34:49], v[198:201], v[226:229], v[34:49]
	v_mfma_f32_32x32x16_bf16 v[18:33], v[198:201], v[234:237], v[18:33]
	s_setprio 0
	s_cmp_lt_i32 s9, 43
	s_cselect_b64 s[10:11], -1, 0
	s_and_b32 s3, s8, -4
	s_cmp_eq_u32 s3, 8
	s_cselect_b64 s[8:9], -1, 0
	s_and_b64 s[8:9], s[10:11], s[8:9]
	s_andn2_b64 vcc, exec, s[8:9]
	s_barrier
